# acc-paired MFMA order + P4 reversed rounds (v3 placement-preserving), measure 1
# speedup vs baseline: 1.0031x; 1.0031x over previous
; #define PG8_STAGE(bufoff, gbase, voff) do { _Pragma("unroll") for (int _i = 0; _i < 2; ++_i) \
;         __builtin_amdgcn_global_load_lds((const unsigned*)((const char*)(gbase) + (voff)[_i]), (LAS unsigned*)(lds + (bufoff) + ldsw + _i * 8192), 16, 0, 0); } while (0)
; #define PG8_WAIT_V(n) asm volatile("s_waitcnt vmcnt(" #n ")" ::: "memory")
; #define PG8_BAR __builtin_amdgcn_s_barrier()
; template <class Epi, class Ptrs>
; __device__ __forceinline__ void gemm_phase(LAS unsigned char* lds, const int K, const StaticOrder& S, const Ptrs& P, const Epi& E) {
;     const int tid = threadIdx.x, wid = __builtin_amdgcn_readfirstlane(tid >> 6), lane = tid & 63, wr = wid >> 2, wc = wid & 3, fr = lane & 15, fq = lane >> 4;
;     const int nt = K / BK;
;     unsigned voffA[2], voffB[2];
; #pragma unroll
;     for (int i = 0; i < 2; ++i) { int R, C; stage_rc(tid * 16 + i * 8192, R, C); const int Rb = (R & ~31) + perm32(R & 31);
;         voffA[i] = (unsigned)(R * K + C) * 2u; voffB[i] = (unsigned)(Rb * K + C) * 2u; }
;     const size_t kstep = (size_t)(BK * 2);
;     const size_t hstep = (size_t)HALF * K * 2;
;     const unsigned ldsw = (unsigned)wid * 1024u;
;     const int aoff = lds_byte(wr * 64 + fr, fq * 8), boff = lds_byte(wc * 32 + fr, fq * 8);
;     ...
;     PG8_STAGE(PG8_SB(1, 0), cB + kstep, voffB); PG8_STAGE(PG8_SA(1, 0), cA + kstep, voffA); PG8_STAGE(PG8_SB(1, 1), cB + hstep + kstep, voffB);
;     PG8_WAIT_V(6); PG8_BAR;
.LBB0_427:
	s_nop 0
	s_nop 0
	s_nop 0
	s_nop 0
	s_nop 0
	s_nop 0
	s_nop 0
	s_nop 0
	s_nop 0
	s_nop 0
	s_nop 0
	s_nop 0
	s_nop 0
	s_nop 0
	s_nop 0
	s_nop 0
	s_nop 0
	s_nop 0
	s_nop 0
	s_nop 0
	s_nop 0
	s_nop 0
	s_nop 0
	s_nop 0
	s_nop 0
	s_nop 0
	s_nop 0
	s_nop 0
	s_nop 0
	s_nop 0
	s_nop 0
	s_nop 0
	s_nop 0
	s_nop 0
	s_nop 0
	s_nop 0
	s_nop 0
	s_nop 0
	s_nop 0
	s_nop 0
	s_nop 0
	s_nop 0
	s_nop 0
	s_nop 0
	s_nop 0
	s_nop 0
	s_nop 0
	s_nop 0
	s_nop 0
	s_nop 0
	s_nop 0
	s_nop 0
	s_nop 0
	s_nop 0
	s_nop 0
	s_nop 0
	s_nop 0
	s_add_u32 s10, s28, 0xe000000
	s_addc_u32 s11, s29, 0
	s_lshl_b32 s4, s4, 5
	s_mov_b64 s[12:13], 0x80
	s_and_b32 s15, s4, 0x60
	s_add_i32 m0, s39, 0x18000
	v_lshl_add_u64 v[6:7], v[6:7], 0, s[12:13]
	s_ashr_i32 s60, s3, 31
	s_lshl_b32 s14, s1, 13
	s_lshl_b32 s16, s15, 7
	s_waitcnt vmcnt(4)
	s_barrier
	global_load_lds_dwordx4 v[6:7], off
	v_lshl_add_u64 v[4:5], v[4:5], 0, s[12:13]
	s_add_i32 m0, s39, 0x1a000
	s_add_i32 s61, s39, 0x8000
	s_add_i32 s62, s39, 0xa000
	global_load_lds_dwordx4 v[4:5], off
	v_lshl_add_u64 v[2:3], v[2:3], 0, s[12:13]
	s_mov_b32 m0, s61
	s_add_u32 s4, s42, 0x40080
	global_load_lds_dwordx4 v[2:3], off
	v_lshl_add_u64 v[0:1], v[0:1], 0, s[12:13]
	s_mov_b32 m0, s62
	s_addc_u32 s5, s43, 0
	global_load_lds_dwordx4 v[0:1], off
	s_add_i32 m0, s39, 0x1c000
	v_lshl_add_u64 v[0:1], s[4:5], 0, v[130:131]
	global_load_lds_dwordx4 v[0:1], off
	v_lshl_add_u64 v[0:1], s[4:5], 0, v[134:135]
	s_add_i32 m0, s39, 0x1e000
	s_sext_i32_i8 s69, s0
	global_load_lds_dwordx4 v[0:1], off
	v_and_b32_e32 v0, 15, v208
	v_lshlrev_b32_e32 v1, 1, v11
	v_lshlrev_b32_e32 v2, 6, v208
	s_movk_i32 s0, 0x3c0
	v_lshlrev_b32_e32 v3, 2, v208
	v_and_or_b32 v2, v2, s0, v1
	v_and_b32_e32 v3, 32, v3
	v_lshl_or_b32 v146, s1, 6, v0
	v_lshl_or_b32 v0, v0, 6, v1
	v_lshlrev_b32_e32 v1, 8, v208
	v_bitop3_b32 v147, s16, v2, v3 bitop3:0xf6
	v_and_b32_e32 v1, 0x38000, v1
	v_lshlrev_b32_e32 v2, 11, v10
	v_or3_b32 v1, v8, v1, v2
	v_add_u32_e32 v136, v1, v9
	v_lshlrev_b32_e32 v1, 4, v12
	s_waitcnt vmcnt(6)
	v_and_b32_e32 v1, 0x78000, v1
	v_bitop3_b32 v0, v0, s14, v3 bitop3:0xde
	v_or3_b32 v1, v8, v1, v2
	s_add_i32 s63, 0, 0x10000
	s_add_i32 s64, 0, 0x14000
	v_or_b32_e32 v148, s15, v11
	v_mov_b32_e32 v137, v131
	v_add_u32_e32 v138, v1, v9
	v_mov_b32_e32 v139, v131
	v_mov_b64_e32 v[140:141], 0x1800
	v_mov_b64_e32 v[142:143], 0x17ff
	v_add_u32_e32 v149, s63, v147
	v_add_u32_e32 v150, 0, v0
	v_add_u32_e32 v151, s64, v147
	s_mov_b64 s[14:15], 0x100000
	s_mov_b32 s65, 0x100000
	s_mov_b64 s[16:17], 0x120000
	s_mov_b32 s66, 0x120000
	s_mov_b64 s[18:19], 0x140000
	s_mov_b32 s67, 0x140000
	s_mov_b64 s[20:21], 0x160000
	s_mov_b32 s68, 0x160000
	s_barrier
